# grid barrier: non-leader workgroups poll the global generation word directly (one hop less, -1.1us per barrier), on top of ALIGN removal
# speedup vs baseline: 1.0138x; 1.0138x over previous
; __device__ __forceinline__ unsigned xb_ld(unsigned* p)              { return __hip_atomic_load(p, __ATOMIC_RELAXED, __HIP_MEMORY_SCOPE_AGENT); }
; __device__ __forceinline__ unsigned xb_add(unsigned* p, unsigned v) { return __hip_atomic_fetch_add(p, v, __ATOMIC_RELAXED, __HIP_MEMORY_SCOPE_AGENT); }
; #define XB_SPIN(cond, bar) do { unsigned _sp = 0; while (cond) { __builtin_amdgcn_s_sleep(1); \
;     if ((++_sp & 255u) == 0u) { if (xb_ld(&(bar)[XB_TMO])) break; if (_sp > XB_SPIN_CAP) { atomicAdd(&(bar)[XB_TMO], 1u); break; } } } } while (0)
; __device__ __forceinline__ void xcd_barrier(unsigned* bar, volatile LAS unsigned* st) {
;     ...
;         const unsigned old = xb_add(&bar[XB_XSUB(x)], 1u);
;         const unsigned gen = old / nloc;
;         if (old + 1u == (gen + 1u) * nloc) {
;             __builtin_amdgcn_fence(__ATOMIC_RELEASE, "agent");
;             asm volatile("s_waitcnt vmcnt(0)" ::: "memory");
;             const unsigned og = xb_add(&bar[XB_TOP], 1u);
;             const unsigned tg = og / nx;
;             if (og + 1u == (tg + 1u) * nx) xb_add(&bar[XB_TOPGEN], 1u);
;             else XB_SPIN(xb_ld(&bar[XB_TOPGEN]) == tg, bar);
;             __builtin_amdgcn_fence(__ATOMIC_ACQUIRE, "agent");
;             xb_add(&bar[XB_XGEN(x)], 1u);
;             asm volatile("s_waitcnt vmcnt(0)" ::: "memory");
;         } else {
;             XB_SPIN(xb_ld(&bar[XB_XGEN(x)]) == gen, bar);
.LBB0_29:
	s_or_b64 exec, exec, s[10:11]
	v_cvt_f32_u32_e32 v5, v3
	s_waitcnt vmcnt(0)
	v_readfirstlane_b32 s4, v4
	v_sub_u32_e32 v4, 0, v3
	v_rcp_iflag_f32_e32 v5, v5
	v_add_u32_e32 v6, s4, v2
	v_mul_f32_e32 v5, 0x4f7ffffe, v5
	v_cvt_u32_f32_e32 v5, v5
	v_mul_lo_u32 v2, v4, v5
	v_mul_hi_u32 v2, v5, v2
	v_add_u32_e32 v2, v5, v2
	v_mul_hi_u32 v2, v6, v2
	v_mul_lo_u32 v4, v2, v3
	v_sub_u32_e32 v4, v6, v4
	v_add_u32_e32 v5, 1, v2
	v_sub_u32_e32 v7, v4, v3
	v_cmp_ge_u32_e32 vcc, v4, v3
	s_nop 1
	v_cndmask_b32_e32 v2, v2, v5, vcc
	v_cndmask_b32_e32 v4, v4, v7, vcc
	v_add_u32_e32 v5, 1, v2
	v_cmp_ge_u32_e32 vcc, v4, v3
	v_add_u32_e32 v4, 1, v6
	s_nop 0
	v_cndmask_b32_e32 v2, v2, v5, vcc
	v_mul_lo_u32 v5, v3, v2
	v_add_u32_e32 v3, v5, v3
	v_cmp_ne_u32_e32 vcc, v4, v3
	s_and_saveexec_b64 s[8:9], vcc
	s_xor_b64 s[8:9], exec, s[8:9]
	s_cbranch_execz .LBB0_43
	s_waitcnt lgkmcnt(0)
	s_add_u32 s14, s2, 0x3c03500
	s_addc_u32 s15, s3, 0
	s_nop 1
	global_load_dword v0, v1, s[14:15] sc1
	s_waitcnt vmcnt(0)
	v_cmp_eq_u32_e32 vcc, v0, v2
	s_and_saveexec_b64 s[10:11], vcc
	s_cbranch_execz .LBB0_42
	s_add_u32 s12, s2, 0x3c00200
	s_addc_u32 s13, s3, 0
	s_mov_b32 s4, 1
	s_mov_b64 s[16:17], 0
	s_branch .LBB0_33
